# v029 + lru_fix_unit carry-scan batch: 16 loads issued together with one wait instead of three serial vmcnt(0) round trips per 8-step batch
# speedup vs baseline: 1.0078x; 1.0002x over previous
; DI void lru_fix_unit(const Ctx& c, int l, int chunk, int half) {
;     ...
;     for (; i + 8 <= n; i += 8) {
;         f32x4 a[8][2];
; #pragma unroll
;         for (int j = 0; j < 8; ++j) { a[j][0] = ag[(size_t)(i + j) * 512]; a[j][1] = ag[(size_t)(i + j) * 512 + 1]; }
; #pragma unroll
;         for (int j = 0; j < 8; ++j) { cr[0] = a[j][0][0] * cr[0] + a[j][0][1]; cr[1] = a[j][0][2] * cr[1] + a[j][0][3]; cr[2] = a[j][1][0] * cr[2] + a[j][1][1]; cr[3] = a[j][1][2] * cr[3] + a[j][1][3]; }
;     }
.LBB0_785:
	v_add_co_u32_e32 v4, vcc, 0xffff1ff0, v60
	s_mov_b32 s9, s12
	s_nop 0
	v_addc_co_u32_e32 v5, vcc, -1, v61, vcc
	global_load_dwordx4 v[20:23], v[4:5], off
	v_add_co_u32_e32 v4, vcc, 0xffff2000, v60
	s_movk_i32 s12, 0x8000
	s_nop 0
	v_addc_co_u32_e32 v5, vcc, -1, v61, vcc
	global_load_dwordx4 v[8:11], v[4:5], off
	v_add_co_u32_e32 v4, vcc, 0xffff3ff0, v60
	v_addc_co_u32_e32 v5, vcc, -1, v61, vcc
	global_load_dwordx4 v[28:31], v[4:5], off
	v_add_co_u32_e32 v4, vcc, 0xffff4000, v60
	s_nop 0
	v_addc_co_u32_e32 v5, vcc, -1, v61, vcc
	global_load_dwordx4 v[12:15], v[4:5], off
	v_add_co_u32_e32 v4, vcc, 0xffff5ff0, v60
	s_nop 0
	v_addc_co_u32_e32 v5, vcc, -1, v61, vcc
	global_load_dwordx4 v[16:19], v[4:5], off
	v_add_co_u32_e32 v4, vcc, 0xffff6000, v60
	s_nop 0
	v_addc_co_u32_e32 v5, vcc, -1, v61, vcc
	v_add_co_u32_e32 v24, vcc, 0xffff7ff0, v60
	global_load_dwordx4 v[4:7], v[4:5], off
	s_nop 0
	v_addc_co_u32_e32 v25, vcc, -1, v61, vcc
	v_add_co_u32_e32 v32, vcc, s12, v60
	s_movk_i32 s12, 0xe000
	s_nop 0
	v_addc_co_u32_e32 v33, vcc, -1, v61, vcc
	v_add_co_u32_e32 v36, vcc, 0xffff9ff0, v60
	global_load_dwordx4 v[32:35], v[32:33], off
	s_nop 0
	v_addc_co_u32_e32 v37, vcc, -1, v61, vcc
	global_load_dwordx4 v[44:47], v[36:37], off
	v_add_co_u32_e32 v36, vcc, 0xffffa000, v60
	global_load_dwordx4 v[24:27], v[24:25], off
	s_nop 0
	v_addc_co_u32_e32 v37, vcc, -1, v61, vcc
	v_add_co_u32_e32 v40, vcc, 0xffffbff0, v60
	global_load_dwordx4 v[36:39], v[36:37], off
	s_nop 0
	v_addc_co_u32_e32 v41, vcc, -1, v61, vcc
	global_load_dwordx4 v[48:51], v[40:41], off
	v_add_co_u32_e32 v40, vcc, 0xffffc000, v60
	v_addc_co_u32_e32 v41, vcc, -1, v61, vcc
	v_add_co_u32_e32 v52, vcc, 0xffffdff0, v60
	global_load_dwordx4 v[40:43], v[40:41], off
	s_nop 0
	v_addc_co_u32_e32 v53, vcc, -1, v61, vcc
	v_add_co_u32_e32 v56, vcc, s12, v60
	global_load_dwordx4 v[52:55], v[52:53], off
	s_nop 0
	v_addc_co_u32_e32 v57, vcc, -1, v61, vcc
	v_add_co_u32_e32 v62, vcc, -16, v60
	global_load_dwordx4 v[56:59], v[56:57], off
	s_nop 0
	v_addc_co_u32_e32 v63, vcc, -1, v61, vcc
	global_load_dwordx4 v[62:65], v[62:63], off
	s_nop 0
	global_load_dwordx4 v[72:75], v[60:61], off
	s_add_i32 s12, s9, 8
	s_add_i32 s9, s9, 16
	v_lshl_add_u64 v[60:61], v[60:61], 0, s[90:91]
	s_cmp_gt_u32 s9, s8
	s_waitcnt vmcnt(0) lgkmcnt(0)
	v_mov_b32_e32 v66, v20
	v_mov_b32_e32 v67, v22
	v_mov_b32_e32 v22, v21
	v_pk_fma_f32 v[20:21], v[70:71], v[66:67], v[22:23]
	v_mov_b32_e32 v22, v28
	v_mov_b32_e32 v23, v30
	v_mov_b32_e32 v30, v29
	v_mov_b32_e32 v28, v8
	v_mov_b32_e32 v29, v10
	v_mov_b32_e32 v10, v9
	v_pk_fma_f32 v[8:9], v[68:69], v[28:29], v[10:11]
	v_mov_b32_e32 v10, v12
	v_mov_b32_e32 v11, v14
	v_mov_b32_e32 v14, v13
	v_pk_fma_f32 v[20:21], v[20:21], v[22:23], v[30:31]
	v_mov_b32_e32 v22, v16
	v_mov_b32_e32 v23, v18
	v_pk_fma_f32 v[8:9], v[8:9], v[10:11], v[14:15]
	v_mov_b32_e32 v10, v4
	v_mov_b32_e32 v11, v6
	v_mov_b32_e32 v18, v17
	v_mov_b32_e32 v6, v5
	v_pk_fma_f32 v[12:13], v[20:21], v[22:23], v[18:19]
	v_mov_b32_e32 v14, v24
	v_mov_b32_e32 v15, v26
	v_mov_b32_e32 v26, v25
	v_pk_fma_f32 v[4:5], v[8:9], v[10:11], v[6:7]
	v_mov_b32_e32 v6, v32
	v_mov_b32_e32 v7, v34
	v_mov_b32_e32 v34, v33
	v_pk_fma_f32 v[12:13], v[12:13], v[14:15], v[26:27]
	v_mov_b32_e32 v14, v44
	v_mov_b32_e32 v15, v46
	v_mov_b32_e32 v46, v45
	v_pk_fma_f32 v[4:5], v[4:5], v[6:7], v[34:35]
	v_mov_b32_e32 v6, v36
	v_mov_b32_e32 v7, v38
	v_mov_b32_e32 v38, v37
	v_pk_fma_f32 v[12:13], v[12:13], v[14:15], v[46:47]
	v_mov_b32_e32 v14, v48
	v_mov_b32_e32 v15, v50
	v_mov_b32_e32 v50, v49
	v_pk_fma_f32 v[4:5], v[4:5], v[6:7], v[38:39]
	v_pk_fma_f32 v[12:13], v[12:13], v[14:15], v[50:51]
	v_mov_b32_e32 v6, v40
	v_mov_b32_e32 v7, v42
	v_mov_b32_e32 v42, v41
	v_pk_fma_f32 v[4:5], v[4:5], v[6:7], v[42:43]
	v_mov_b32_e32 v14, v52
	v_mov_b32_e32 v15, v54
	v_mov_b32_e32 v54, v53
	v_pk_fma_f32 v[12:13], v[12:13], v[14:15], v[54:55]
	v_mov_b32_e32 v6, v56
	v_mov_b32_e32 v7, v58
	v_mov_b32_e32 v58, v57
	v_mov_b32_e32 v14, v62
	v_mov_b32_e32 v15, v64
	v_mov_b32_e32 v64, v63
	v_pk_fma_f32 v[4:5], v[4:5], v[6:7], v[58:59]
	v_mov_b32_e32 v6, v72
	v_mov_b32_e32 v7, v74
	v_mov_b32_e32 v74, v73
	v_pk_fma_f32 v[70:71], v[12:13], v[14:15], v[64:65]
	v_pk_fma_f32 v[68:69], v[4:5], v[6:7], v[74:75]
	s_cbranch_scc0 .LBB0_785
	s_cmp_ge_u32 s12, s8
	s_cbranch_scc0 .LBB0_788
	s_branch .LBB0_790
